# stack17 + C-layer attention epilogue through a wave-private LDS tile: every output store writes eight whole 128-byte rows (layout unchanged)
# speedup vs baseline: 1.0039x; 1.0039x over previous
.LBB0_250:
	v_and_b32_e32 v3, 64, v158
	v_xor_b32_e32 v2, 32, v158
	v_add_u32_e32 v3, 64, v3
	s_lshl_b64 s[98:99], s[60:61], 25
	v_cmp_lt_i32_e32 vcc, v2, v3
	s_add_u32 s67, s70, s98
	s_addc_u32 s73, s71, s99
	v_cndmask_b32_e32 v2, v158, v2, vcc
	v_lshlrev_b32_e32 v91, 2, v2
	s_add_u32 s67, s67, 0xfe000000
	ds_bpermute_b32 v2, v91, v138
	s_addc_u32 s73, s73, -1
	s_cmp_eq_u32 s60, 0
	s_cselect_b32 s67, s30, s67
	s_cselect_b32 s73, s31, s73
	s_add_u32 s64, s67, s64
	s_addc_u32 s65, s73, s65
	v_mov_b32_e32 v93, v1
	s_waitcnt lgkmcnt(0)
	v_add_f32_e32 v2, v138, v2
	v_lshl_add_u64 v[96:97], s[64:65], 0, v[92:93]
	v_div_scale_f32 v3, s[64:65], v2, v2, 1.0
	v_rcp_f32_e32 v4, v3
	s_lshl_b64 s[60:61], s[60:61], 20
	s_add_u32 s60, s96, s60
	s_addc_u32 s61, s97, s61
	v_fma_f32 v5, -v3, v4, 1.0
	v_fmac_f32_e32 v4, v5, v4
	v_div_scale_f32 v5, vcc, 1.0, v2, 1.0
	v_mul_f32_e32 v6, v5, v4
	v_fma_f32 v7, -v3, v6, v5
	v_fmac_f32_e32 v6, v7, v4
	v_fma_f32 v3, -v3, v6, v5
	v_div_fmas_f32 v3, v3, v4, v6
	v_div_fixup_f32 v3, v3, v2, 1.0
	v_readlane_b32 s100, v248, 28
	s_nop 0
	s_cmp_eq_u32 s100, 3
	s_cbranch_scc1 .LattnA_0
	s_add_u32 s0, s60, s0
	s_addc_u32 s1, s61, s1
	v_mul_f32_e32 v218, v16, v3
	v_mul_f32_e32 v219, v17, v3
	v_cvt_pk_bf16_f32 v200, v218, v219
	v_mul_f32_e32 v218, v18, v3
	v_mul_f32_e32 v219, v19, v3
	v_cvt_pk_bf16_f32 v201, v218, v219
	v_mul_f32_e32 v218, v32, v3
	v_mul_f32_e32 v219, v33, v3
	v_cvt_pk_bf16_f32 v208, v218, v219
	v_mul_f32_e32 v218, v34, v3
	v_mul_f32_e32 v219, v35, v3
	v_cvt_pk_bf16_f32 v209, v218, v219
	v_mul_f32_e32 v218, v20, v3
	v_mul_f32_e32 v219, v21, v3
	v_cvt_pk_bf16_f32 v202, v218, v219
	v_mul_f32_e32 v218, v22, v3
	v_mul_f32_e32 v219, v23, v3
	v_cvt_pk_bf16_f32 v203, v218, v219
	v_mul_f32_e32 v218, v36, v3
	v_mul_f32_e32 v219, v37, v3
	v_cvt_pk_bf16_f32 v210, v218, v219
	v_mul_f32_e32 v218, v38, v3
	v_mul_f32_e32 v219, v39, v3
	v_cvt_pk_bf16_f32 v211, v218, v219
	v_mul_f32_e32 v218, v24, v3
	v_mul_f32_e32 v219, v25, v3
	v_cvt_pk_bf16_f32 v204, v218, v219
	v_mul_f32_e32 v218, v26, v3
	v_mul_f32_e32 v219, v27, v3
	v_cvt_pk_bf16_f32 v205, v218, v219
	v_mul_f32_e32 v218, v40, v3
	v_mul_f32_e32 v219, v41, v3
	v_cvt_pk_bf16_f32 v212, v218, v219
	v_mul_f32_e32 v218, v42, v3
	v_mul_f32_e32 v219, v43, v3
	v_cvt_pk_bf16_f32 v213, v218, v219
	v_mul_f32_e32 v218, v28, v3
	v_mul_f32_e32 v219, v29, v3
	v_cvt_pk_bf16_f32 v206, v218, v219
	v_mul_f32_e32 v218, v30, v3
	v_mul_f32_e32 v219, v31, v3
	v_cvt_pk_bf16_f32 v207, v218, v219
	v_mul_f32_e32 v218, v44, v3
	v_mul_f32_e32 v219, v45, v3
	v_cvt_pk_bf16_f32 v214, v218, v219
	v_mul_f32_e32 v218, v46, v3
	v_mul_f32_e32 v219, v47, v3
	v_cvt_pk_bf16_f32 v215, v218, v219
	v_lshrrev_b32_e32 v216, 5, v158
	v_and_b32_e32 v217, 15, v158
	v_lshrrev_b32_e32 v218, 6, v150
	v_mul_u32_u24_e32 v218, 0x900, v218
	v_mul_u32_u24_e32 v219, 0x90, v217
	v_mov_b32_e32 v221, 0x22450
	v_lshl_add_u32 v220, v216, 4, v219
	v_add3_u32 v220, v220, v218, v221
	v_lshrrev_b32_e32 v223, 3, v158
	v_and_b32_e32 v224, 7, v158
	v_mul_u32_u24_e32 v222, 0x90, v223
	v_lshl_add_u32 v222, v224, 4, v222
	v_add3_u32 v222, v222, v218, v221
	v_lshlrev_b32_e32 v228, 4, v224
	v_lshlrev_b32_e32 v229, 3, v216
	v_sub_u32_e32 v228, v228, v229
	v_ashrrev_i32_e32 v229, 31, v228
	v_lshl_add_u64 v[226:227], v[96:97], 0, v[228:229]
	v_readlane_b32 s100, v94, 0
	v_readlane_b32 s101, v95, 0
	v_permlane32_swap_b32_e32 v200, v202
	v_permlane32_swap_b32_e32 v201, v203
	v_permlane32_swap_b32_e32 v204, v206
	v_permlane32_swap_b32_e32 v205, v207
	v_permlane32_swap_b32_e32 v208, v210
	v_permlane32_swap_b32_e32 v209, v211
	v_permlane32_swap_b32_e32 v212, v214
	v_permlane32_swap_b32_e32 v213, v215
	s_mov_b32 exec_lo, 0xffff
	s_mov_b32 exec_hi, 0xffff
	ds_write_b128 v220, v[200:203]
	ds_write_b128 v220, v[204:207] offset:32
	ds_write_b128 v220, v[208:211] offset:64
	ds_write_b128 v220, v[212:215] offset:96
	s_mov_b64 exec, -1
	s_waitcnt lgkmcnt(0)
	ds_read_b128 v[230:233], v222
	ds_read_b128 v[234:237], v222 offset:1152
	v_add_u32_e32 v238, 0, v223
	v_mov_b32_e32 v240, s100
	v_mov_b32_e32 v241, s101
	v_mad_u64_u32 v[240:241], vcc, v238, s93, v[240:241]
	v_lshlrev_b64 v[240:241], 11, v[240:241]
	v_lshl_add_u64 v[240:241], v[240:241], 0, v[226:227]
	v_add_u32_e32 v238, 8, v223
	v_mov_b32_e32 v242, s100
	v_mov_b32_e32 v243, s101
	v_mad_u64_u32 v[242:243], vcc, v238, s93, v[242:243]
	v_lshlrev_b64 v[242:243], 11, v[242:243]
	v_lshl_add_u64 v[242:243], v[242:243], 0, v[226:227]
	s_waitcnt lgkmcnt(1)
	global_store_dwordx4 v[240:241], v[230:233], off
	s_waitcnt lgkmcnt(0)
	global_store_dwordx4 v[242:243], v[234:237], off
	s_mov_b32 exec_lo, 0xffff0000
	s_mov_b32 exec_hi, 0xffff0000
	ds_write_b128 v220, v[200:203]
	ds_write_b128 v220, v[204:207] offset:32
	ds_write_b128 v220, v[208:211] offset:64
	ds_write_b128 v220, v[212:215] offset:96
	s_mov_b64 exec, -1
	s_waitcnt lgkmcnt(0)
	ds_read_b128 v[230:233], v222
	ds_read_b128 v[234:237], v222 offset:1152
	v_add_u32_e32 v238, 16, v223
	v_mov_b32_e32 v240, s100
	v_mov_b32_e32 v241, s101
	v_mad_u64_u32 v[240:241], vcc, v238, s93, v[240:241]
	v_lshlrev_b64 v[240:241], 11, v[240:241]
	v_lshl_add_u64 v[240:241], v[240:241], 0, v[226:227]
	v_add_u32_e32 v238, 24, v223
	v_mov_b32_e32 v242, s100
	v_mov_b32_e32 v243, s101
	v_mad_u64_u32 v[242:243], vcc, v238, s93, v[242:243]
	v_lshlrev_b64 v[242:243], 11, v[242:243]
	v_lshl_add_u64 v[242:243], v[242:243], 0, v[226:227]
	s_waitcnt lgkmcnt(1)
	global_store_dwordx4 v[240:241], v[230:233], off
	s_waitcnt lgkmcnt(0)
	global_store_dwordx4 v[242:243], v[234:237], off
	s_branch .LattnJ_0

.LBB0_263:
	ds_bpermute_b32 v2, v91, v93
	s_waitcnt lgkmcnt(0)
	v_add_f32_e32 v2, v93, v2
	v_div_scale_f32 v3, s[16:17], v2, v2, 1.0
	v_rcp_f32_e32 v4, v3
	s_nop 0
	v_fma_f32 v5, -v3, v4, 1.0
	v_fmac_f32_e32 v4, v5, v4
	v_div_scale_f32 v5, vcc, 1.0, v2, 1.0
	v_mul_f32_e32 v6, v5, v4
	v_fma_f32 v7, -v3, v6, v5
	v_fmac_f32_e32 v6, v7, v4
	v_fma_f32 v3, -v3, v6, v5
	v_div_fmas_f32 v3, v3, v4, v6
	v_div_fixup_f32 v3, v3, v2, 1.0
	v_readlane_b32 s100, v248, 28
	s_nop 0
	s_cmp_eq_u32 s100, 3
	s_cbranch_scc1 .LattnA_1
	v_mul_f32_e32 v218, v16, v3
	v_mul_f32_e32 v219, v17, v3
	v_cvt_pk_bf16_f32 v200, v218, v219
	v_mul_f32_e32 v218, v18, v3
	v_mul_f32_e32 v219, v19, v3
	v_cvt_pk_bf16_f32 v201, v218, v219
	v_mul_f32_e32 v218, v32, v3
	v_mul_f32_e32 v219, v33, v3
	v_cvt_pk_bf16_f32 v208, v218, v219
	v_mul_f32_e32 v218, v34, v3
	v_mul_f32_e32 v219, v35, v3
	v_cvt_pk_bf16_f32 v209, v218, v219
	v_mul_f32_e32 v218, v20, v3
	v_mul_f32_e32 v219, v21, v3
	v_cvt_pk_bf16_f32 v202, v218, v219
	v_mul_f32_e32 v218, v22, v3
	v_mul_f32_e32 v219, v23, v3
	v_cvt_pk_bf16_f32 v203, v218, v219
	v_mul_f32_e32 v218, v36, v3
	v_mul_f32_e32 v219, v37, v3
	v_cvt_pk_bf16_f32 v210, v218, v219
	v_mul_f32_e32 v218, v38, v3
	v_mul_f32_e32 v219, v39, v3
	v_cvt_pk_bf16_f32 v211, v218, v219
	v_mul_f32_e32 v218, v24, v3
	v_mul_f32_e32 v219, v25, v3
	v_cvt_pk_bf16_f32 v204, v218, v219
	v_mul_f32_e32 v218, v26, v3
	v_mul_f32_e32 v219, v27, v3
	v_cvt_pk_bf16_f32 v205, v218, v219
	v_mul_f32_e32 v218, v40, v3
	v_mul_f32_e32 v219, v41, v3
	v_cvt_pk_bf16_f32 v212, v218, v219
	v_mul_f32_e32 v218, v42, v3
	v_mul_f32_e32 v219, v43, v3
	v_cvt_pk_bf16_f32 v213, v218, v219
	v_mul_f32_e32 v218, v28, v3
	v_mul_f32_e32 v219, v29, v3
	v_cvt_pk_bf16_f32 v206, v218, v219
	v_mul_f32_e32 v218, v30, v3
	v_mul_f32_e32 v219, v31, v3
	v_cvt_pk_bf16_f32 v207, v218, v219
	v_mul_f32_e32 v218, v44, v3
	v_mul_f32_e32 v219, v45, v3
	v_cvt_pk_bf16_f32 v214, v218, v219
	v_mul_f32_e32 v218, v46, v3
	v_mul_f32_e32 v219, v47, v3
	v_cvt_pk_bf16_f32 v215, v218, v219
	v_lshrrev_b32_e32 v216, 5, v158
	v_and_b32_e32 v217, 15, v158
	v_lshrrev_b32_e32 v218, 6, v150
	v_mul_u32_u24_e32 v218, 0x900, v218
	v_mul_u32_u24_e32 v219, 0x90, v217
	v_mov_b32_e32 v221, 0x22450
	v_lshl_add_u32 v220, v216, 4, v219
	v_add3_u32 v220, v220, v218, v221
	v_lshrrev_b32_e32 v223, 3, v158
	v_and_b32_e32 v224, 7, v158
	v_mul_u32_u24_e32 v222, 0x90, v223
	v_lshl_add_u32 v222, v224, 4, v222
	v_add3_u32 v222, v222, v218, v221
	v_lshlrev_b32_e32 v228, 4, v224
	v_lshlrev_b32_e32 v229, 3, v216
	v_sub_u32_e32 v228, v228, v229
	v_ashrrev_i32_e32 v229, 31, v228
	v_lshl_add_u64 v[226:227], v[96:97], 0, v[228:229]
	v_readlane_b32 s100, v94, 0
	v_readlane_b32 s101, v95, 0
	v_permlane32_swap_b32_e32 v200, v202
	v_permlane32_swap_b32_e32 v201, v203
	v_permlane32_swap_b32_e32 v204, v206
	v_permlane32_swap_b32_e32 v205, v207
	v_permlane32_swap_b32_e32 v208, v210
	v_permlane32_swap_b32_e32 v209, v211
	v_permlane32_swap_b32_e32 v212, v214
	v_permlane32_swap_b32_e32 v213, v215
	s_mov_b32 exec_lo, 0xffff
	s_mov_b32 exec_hi, 0xffff
	ds_write_b128 v220, v[200:203]
	ds_write_b128 v220, v[204:207] offset:32
	ds_write_b128 v220, v[208:211] offset:64
	ds_write_b128 v220, v[212:215] offset:96
	s_mov_b64 exec, -1
	s_waitcnt lgkmcnt(0)
	ds_read_b128 v[230:233], v222
	ds_read_b128 v[234:237], v222 offset:1152
	v_add_u32_e32 v238, 0, v223
	v_mov_b32_e32 v240, s100
	v_mov_b32_e32 v241, s101
	v_mad_u64_u32 v[240:241], vcc, v238, s93, v[240:241]
	v_lshlrev_b64 v[240:241], 11, v[240:241]
	v_lshl_add_u64 v[240:241], v[240:241], 0, v[226:227]
	v_add_u32_e32 v238, 8, v223
	v_mov_b32_e32 v242, s100
	v_mov_b32_e32 v243, s101
	v_mad_u64_u32 v[242:243], vcc, v238, s93, v[242:243]
	v_lshlrev_b64 v[242:243], 11, v[242:243]
	v_lshl_add_u64 v[242:243], v[242:243], 0, v[226:227]
	s_waitcnt lgkmcnt(1)
	global_store_dwordx4 v[240:241], v[230:233], off
	s_waitcnt lgkmcnt(0)
	global_store_dwordx4 v[242:243], v[234:237], off
	s_mov_b32 exec_lo, 0xffff0000
	s_mov_b32 exec_hi, 0xffff0000
	ds_write_b128 v220, v[200:203]
	ds_write_b128 v220, v[204:207] offset:32
	ds_write_b128 v220, v[208:211] offset:64
	ds_write_b128 v220, v[212:215] offset:96
	s_mov_b64 exec, -1
	s_waitcnt lgkmcnt(0)
	ds_read_b128 v[230:233], v222
	ds_read_b128 v[234:237], v222 offset:1152
	v_add_u32_e32 v238, 16, v223
	v_mov_b32_e32 v240, s100
	v_mov_b32_e32 v241, s101
	v_mad_u64_u32 v[240:241], vcc, v238, s93, v[240:241]
	v_lshlrev_b64 v[240:241], 11, v[240:241]
	v_lshl_add_u64 v[240:241], v[240:241], 0, v[226:227]
	v_add_u32_e32 v238, 24, v223
	v_mov_b32_e32 v242, s100
	v_mov_b32_e32 v243, s101
	v_mad_u64_u32 v[242:243], vcc, v238, s93, v[242:243]
	v_lshlrev_b64 v[242:243], 11, v[242:243]
	v_lshl_add_u64 v[242:243], v[242:243], 0, v[226:227]
	s_waitcnt lgkmcnt(1)
	global_store_dwordx4 v[240:241], v[230:233], off
	s_waitcnt lgkmcnt(0)
	global_store_dwordx4 v[242:243], v[234:237], off
	s_branch .LattnJ_1
